# HGRN phase C backward-direction output stage: four gnorm_w loads issued together into free VGPRs with one wait (was load+vmcnt(0) per row group, each also waiting on the previous store ack)
# baseline (speedup 1.0000x reference)
; #define LAS __attribute__((address_space(3)))
; __device__ __forceinline__ unsigned pk2(float lo, float hi) { const f32x2 v = {lo, hi}; const bf16x2_t b = __builtin_convertvector(v, bf16x2_t); return __builtin_bit_cast(unsigned, b); }
; __device__ __forceinline__ float rsqrtf_(float x) { return __builtin_amdgcn_rsqf(x); }
; template <int DIR>
; __device__ __forceinline__ void hgrn_c_dir(const Frame& F, int l, int it_lat  , int h, int row0, bf16_t* QV, unsigned* ofs  , bool dry,
;                                            unsigned (&rf)[8], unsigned (&rq)[8], unsigned (&rv)[8], bool pre, int itn  ) {
;     ...
;             LAS float* rms = (LAS float*)(L + hg::O_RMS) + (32 * tb + r) * 4;
;             if (hh == 0) rms[ebo] = ss;
;             __syncthreads();
;             const f32x4 q4 = *(const LAS f32x4*)rms;
;             const float rs = rsqrtf_(((q4.x + q4.y) + (q4.z + q4.w)) * (1.0f / HD) + EPS);
;             const float* gwp = F.a->in[9] + (size_t)l * HD + 32 * ebo + 4 * hh;
;             bf16_t* op = QV + (size_t)(rowc + 32 * tb) * 2048 + h * 128 + 32 * ebo;
;             const unsigned loff = (unsigned)(r * 2048 + 4 * hh);
; #pragma unroll
;             for (int g = 0; g < 4; ++g) {
;                 const f32x4 gw = *(const f32x4*)(gwp + 8 * g);
;                 u32x2 ov; ov.x = pk2(o[4 * g] * rs * gw.x, o[4 * g + 1] * rs * gw.y); ov.y = pk2(o[4 * g + 2] * rs * gw.z, o[4 * g + 3] * rs * gw.w);
;                 if (!dry) *(u32x2*)(op + loff + 8 * g) = ov; else asm volatile("" :: "v"(ov));
.LBB0_802:
	s_or_b64 exec, exec, s[16:17]
	s_waitcnt lgkmcnt(0)
	s_barrier
	ds_read_b128 v[48:51], v48
	s_add_i32 s16, s30, s33
	s_ashr_i32 s17, s16, 31
	s_lshl_b64 s[16:17], s[16:17], 12
	s_add_u32 s16, s5, s16
	s_waitcnt lgkmcnt(0)
	v_mov_b32_e32 v52, v49
	v_mov_b32_e32 v53, v50
	v_mov_b32_e32 v49, v51
	v_pk_add_f32 v[48:49], v[52:53], v[48:49]
	v_lshlrev_b32_e32 v52, 2, v177
	v_ashrrev_i32_e32 v53, 31, v52
	v_lshl_add_u64 v[50:51], v[52:53], 2, s[88:89]
	global_load_dwordx4 v[54:57], v[50:51], off
	global_load_dwordx4 v[210:213], v[50:51], off offset:32
	global_load_dwordx4 v[214:217], v[50:51], off offset:64
	global_load_dwordx4 v[218:221], v[50:51], off offset:96
	v_add_f32_e32 v48, v48, v49
	v_fmamk_f32 v48, v48, 0x3c000000, v204
	v_rsq_f32_e32 v48, v48
	s_addc_u32 s17, s11, s17
	s_and_b64 vcc, exec, s[0:1]
	v_pk_mul_f32 v[58:59], v[88:89], v[48:49] op_sel_hi:[1,0]
	s_waitcnt vmcnt(0)
	v_pk_mul_f32 v[54:55], v[54:55], v[58:59]
	v_pk_mul_f32 v[58:59], v[86:87], v[48:49] op_sel_hi:[1,0]
	v_cvt_pk_bf16_f32 v54, v54, v55
	v_pk_mul_f32 v[56:57], v[56:57], v[58:59]
	s_nop 0
	v_cvt_pk_bf16_f32 v55, v56, v57
	s_cbranch_vccz .LBB0_813
	v_lshl_add_u32 v0, v0, 11, v52
	v_lshl_add_u64 v[52:53], v[0:1], 1, s[16:17]
	s_cbranch_execnz .LBB0_805

; __device__ __forceinline__ unsigned pk2(float lo, float hi) { const f32x2 v = {lo, hi}; const bf16x2_t b = __builtin_convertvector(v, bf16x2_t); return __builtin_bit_cast(unsigned, b); }
; template <int DIR>
; __device__ __forceinline__ void hgrn_c_dir(const Frame& F, int l, int it_lat  , int h, int row0, bf16_t* QV, unsigned* ofs  , bool dry,
;                                            unsigned (&rf)[8], unsigned (&rq)[8], unsigned (&rv)[8], bool pre, int itn  ) {
;     ...
;             for (int g = 0; g < 4; ++g) {
;                 const f32x4 gw = *(const f32x4*)(gwp + 8 * g);
;                 u32x2 ov; ov.x = pk2(o[4 * g] * rs * gw.x, o[4 * g + 1] * rs * gw.y); ov.y = pk2(o[4 * g + 2] * rs * gw.z, o[4 * g + 3] * rs * gw.w);
;                 if (!dry) *(u32x2*)(op + loff + 8 * g) = ov; else asm volatile("" :: "v"(ov));
.LBB0_805:
	v_mov_b32_e32 v49, v48
	v_pk_mul_f32 v[10:11], v[10:11], v[48:49]
	v_pk_mul_f32 v[12:13], v[12:13], v[48:49]
	s_and_b64 vcc, exec, s[0:1]
	v_pk_mul_f32 v[10:11], v[10:11], v[210:211]
	v_pk_mul_f32 v[12:13], v[12:13], v[212:213]
	v_cvt_pk_bf16_f32 v10, v10, v11
	v_cvt_pk_bf16_f32 v11, v12, v13
	s_cbranch_vccz .LBB0_814
	s_cbranch_execnz .LBB0_808

; __device__ __forceinline__ unsigned pk2(float lo, float hi) { const f32x2 v = {lo, hi}; const bf16x2_t b = __builtin_convertvector(v, bf16x2_t); return __builtin_bit_cast(unsigned, b); }
; template <int DIR>
; __device__ __forceinline__ void hgrn_c_dir(const Frame& F, int l, int it_lat  , int h, int row0, bf16_t* QV, unsigned* ofs  , bool dry,
;                                            unsigned (&rf)[8], unsigned (&rq)[8], unsigned (&rv)[8], bool pre, int itn  ) {
;     ...
;             for (int g = 0; g < 4; ++g) {
;                 const f32x4 gw = *(const f32x4*)(gwp + 8 * g);
;                 u32x2 ov; ov.x = pk2(o[4 * g] * rs * gw.x, o[4 * g + 1] * rs * gw.y); ov.y = pk2(o[4 * g + 2] * rs * gw.z, o[4 * g + 3] * rs * gw.w);
;                 if (!dry) *(u32x2*)(op + loff + 8 * g) = ov; else asm volatile("" :: "v"(ov));
.LBB0_808:
	v_pk_mul_f32 v[8:9], v[8:9], v[48:49]
	v_pk_mul_f32 v[6:7], v[6:7], v[48:49]
	s_and_b64 vcc, exec, s[0:1]
	v_pk_mul_f32 v[8:9], v[8:9], v[214:215]
	v_pk_mul_f32 v[10:11], v[6:7], v[216:217]
	v_cvt_pk_bf16_f32 v6, v8, v9
	v_cvt_pk_bf16_f32 v7, v10, v11
	s_cbranch_vccz .LBB0_815
	s_cbranch_execnz .LBB0_811

; __device__ __forceinline__ unsigned pk2(float lo, float hi) { const f32x2 v = {lo, hi}; const bf16x2_t b = __builtin_convertvector(v, bf16x2_t); return __builtin_bit_cast(unsigned, b); }
; template <int DIR>
; __device__ __forceinline__ void hgrn_c_dir(const Frame& F, int l, int it_lat  , int h, int row0, bf16_t* QV, unsigned* ofs  , bool dry,
;                                            unsigned (&rf)[8], unsigned (&rq)[8], unsigned (&rv)[8], bool pre, int itn  ) {
;     ...
;             for (int g = 0; g < 4; ++g) {
;                 const f32x4 gw = *(const f32x4*)(gwp + 8 * g);
;                 u32x2 ov; ov.x = pk2(o[4 * g] * rs * gw.x, o[4 * g + 1] * rs * gw.y); ov.y = pk2(o[4 * g + 2] * rs * gw.z, o[4 * g + 3] * rs * gw.w);
;                 if (!dry) *(u32x2*)(op + loff + 8 * g) = ov; else asm volatile("" :: "v"(ov));
.LBB0_811:
	v_pk_mul_f32 v[2:3], v[2:3], v[48:49]
	v_pk_mul_f32 v[4:5], v[4:5], v[48:49]
	s_and_b64 vcc, exec, s[0:1]
	v_pk_mul_f32 v[2:3], v[2:3], v[218:219]
	v_pk_mul_f32 v[4:5], v[4:5], v[220:221]
	v_cvt_pk_bf16_f32 v2, v2, v3
	v_cvt_pk_bf16_f32 v3, v4, v5
	s_cbranch_vccz .LBB0_816
	s_cbranch_execnz .LBB0_785
	s_branch .LBB0_817
